# split-phase grid barrier between in-projection and mixers: arrive after first tile / at phase end, waits at LRU-A start / before the SGU-conv queue
# speedup vs baseline: 1.0058x; 1.0058x over previous
.LBB0_218:
	v_readlane_b32 s8, v244, 2
	v_readlane_b32 s9, v244, 3
	s_add_u32 s11, s8, 0x3900000
	s_addc_u32 s12, s9, 0
	s_add_u32 s4, s8, 0x7900000
	s_addc_u32 s5, s9, 0
	v_writelane_b32 v244, s4, 4
	s_load_dwordx2 s[94:95], s[52:53], 0x10
	s_load_dwordx4 s[44:47], s[52:53], 0x48
	v_writelane_b32 v244, s5, 5
	s_add_u32 s4, s8, 0x15eb4000
	v_writelane_b32 v244, s4, 6
	s_addc_u32 s4, s9, 0
	v_writelane_b32 v244, s4, 7
	s_add_u32 s4, s8, 0x15ea0000
	v_writelane_b32 v244, s4, 8
	s_addc_u32 s4, s9, 0
	s_and_b32 s98, s2, 63
	s_cmp_lt_u32 s98, 13
	s_cselect_b32 s98, 1, 0
	s_and_b32 s99, s2, 1
	s_or_b32 s98, s98, s99
	s_cmp_eq_u32 s98, 0
	v_writelane_b32 v244, s4, 9
	s_cselect_b64 s[4:5], -1, 0
	v_writelane_b32 v244, s4, 10
	s_cmp_lg_u32 s98, 0
	v_lshrrev_b32_e32 v1, 20, v0
	v_writelane_b32 v244, s5, 11
	s_cselect_b64 s[4:5], -1, 0
	v_writelane_b32 v244, s4, 12
	s_cmpk_lt_i32 s2, 0x100
	v_lshrrev_b32_e32 v0, 10, v0
	v_writelane_b32 v244, s5, 13
	s_cselect_b64 s[4:5], -1, 0
	v_writelane_b32 v244, s4, 14
	s_cmpk_lt_i32 s2, 0x500
	v_or_b32_e32 v0, v0, v1
	v_writelane_b32 v244, s5, 15
	s_cselect_b64 s[4:5], -1, 0
	v_writelane_b32 v244, s4, 16
	s_ashr_i32 s66, s2, 31
	s_ashr_i32 s67, s80, 31
	v_writelane_b32 v244, s5, 17
	s_lshr_b32 s4, s66, 29
	s_add_i32 s5, s2, s4
	s_ashr_i32 s4, s5, 3
	s_and_b32 s5, s5, -8
	s_sub_i32 s5, s2, s5
	s_cmp_lt_i32 s70, 0
	s_cselect_b64 s[6:7], -1, 0
	s_add_u32 s14, s68, 0x16370f00
	s_addc_u32 s15, s69, 0
	s_add_u32 s16, s68, 0x16371100
	s_addc_u32 s17, s69, 0
	s_add_u32 s58, s68, 0x16371200
	v_writelane_b32 v244, s6, 18
	s_addc_u32 s59, s69, 0
	s_mul_i32 s81, s81, s80
	v_writelane_b32 v244, s7, 19
	s_add_u32 s6, s68, 0x16371300
	s_addc_u32 s7, s69, 0
	v_writelane_b32 v244, s6, 20
	s_mov_b32 s93, 0
	v_mbcnt_lo_u32_b32 v1, -1, 0
	v_writelane_b32 v244, s7, 21
	s_add_u32 s6, s68, 0x16371400
	s_addc_u32 s7, s69, 0
	v_writelane_b32 v244, s6, 22
	v_mov_b32_e32 v145, 0
	v_mov_b32_e32 v176, 0x358637bd
	v_writelane_b32 v244, s7, 23
	s_add_u32 s6, s68, 0x16371500
	s_addc_u32 s7, s69, 0
	v_writelane_b32 v244, s6, 24
	v_mov_b32_e32 v177, 0x260
	v_mov_b32_e32 v178, 1
	v_writelane_b32 v244, s7, 25
	s_add_u32 s6, s68, 0x16371600
	s_addc_u32 s7, s69, 0
	v_writelane_b32 v244, s6, 26
	v_mov_b32_e32 v179, 0x3ecc95a3
	v_mbcnt_hi_u32_b32 v180, -1, v1
	v_writelane_b32 v244, s7, 27
	s_add_u32 s6, s68, 0x16371700
	s_addc_u32 s7, s69, 0
	v_writelane_b32 v244, s6, 28
	v_mov_b64_e32 v[146:147], 0x500
	v_mov_b64_e32 v[148:149], 0x4ff
	v_writelane_b32 v244, s7, 29
	s_add_u32 s6, s68, 0x16371800
	s_addc_u32 s7, s69, 0
	v_writelane_b32 v244, s6, 30
	v_mov_b32_e32 v181, 0x82
	v_mov_b32_e32 v182, 0x7f800000
	v_writelane_b32 v244, s7, 31
	s_add_u32 s6, s68, 0x16371900
	s_addc_u32 s7, s69, 0
	s_add_u32 s34, s68, 0x16371a00
	s_addc_u32 s35, s69, 0
	s_add_u32 s36, s68, 0x16371b00
	s_addc_u32 s37, s69, 0
	s_add_u32 s18, s68, 0x16371c00
	s_addc_u32 s19, s69, 0
	s_add_u32 s20, s68, 0x16371d00
	s_addc_u32 s21, s69, 0
	s_add_u32 s22, s68, 0x16371e00
	s_addc_u32 s23, s69, 0
	s_add_u32 s24, s68, 0x16371f00
	s_addc_u32 s25, s69, 0
	s_add_u32 s26, s68, 0x16372000
	s_addc_u32 s27, s69, 0
	v_writelane_b32 v244, s6, 32
	s_cmp_eq_u32 s33, 15
	v_mov_b32_e32 v183, 0x7fc00000
	v_writelane_b32 v244, s7, 33
	s_cselect_b64 s[6:7], -1, 0
	v_writelane_b32 v244, s6, 34
	s_cmp_eq_u32 s33, 14
	v_mov_b32_e32 v184, 0xff800000
	v_writelane_b32 v244, s7, 35
	s_cselect_b64 s[6:7], -1, 0
	v_writelane_b32 v244, s6, 36
	s_cmp_eq_u32 s33, 13
	v_mov_b32_e32 v185, 0xc00
	v_writelane_b32 v244, s7, 37
	s_cselect_b64 s[6:7], -1, 0
	v_writelane_b32 v244, s6, 38
	s_cmp_eq_u32 s33, 12
	v_mov_b32_e32 v186, 0x800
	v_writelane_b32 v244, s7, 39
	s_cselect_b64 s[6:7], -1, 0
	v_writelane_b32 v244, s6, 40
	s_cmp_eq_u32 s33, 11
	v_mov_b32_e32 v187, 0x400
	v_writelane_b32 v244, s7, 41
	s_cselect_b64 s[6:7], -1, 0
	v_writelane_b32 v244, s6, 42
	s_cmp_eq_u32 s33, 10
	v_mov_b64_e32 v[150:151], 0x200
	v_writelane_b32 v244, s7, 43
	s_cselect_b64 s[6:7], -1, 0
	v_writelane_b32 v244, s6, 44
	s_cmp_eq_u32 s33, 9
	v_mov_b64_e32 v[152:153], 0x1ff
	v_writelane_b32 v244, s7, 45
	s_cselect_b64 s[6:7], -1, 0
	v_writelane_b32 v244, s6, 46
	s_cmp_eq_u32 s33, 8
	v_mov_b64_e32 v[154:155], 0x15ec4800
	v_writelane_b32 v244, s7, 47
	s_cselect_b64 s[6:7], -1, 0
	v_writelane_b32 v244, s6, 48
	s_cmp_eq_u32 s33, 7
	s_mov_b32 s84, 0x66666667
	v_writelane_b32 v244, s7, 49
	s_cselect_b64 s[6:7], -1, 0
	v_writelane_b32 v244, s6, 50
	s_cmp_eq_u32 s33, 6
	s_movk_i32 s62, 0x2800
	v_writelane_b32 v244, s7, 51
	s_cselect_b64 s[6:7], -1, 0
	v_writelane_b32 v244, s6, 52
	s_cmp_eq_u32 s33, 5
	s_mov_b32 s63, 0x10000
	v_writelane_b32 v244, s7, 53
	s_cselect_b64 s[6:7], -1, 0
	v_writelane_b32 v244, s6, 54
	s_cmp_eq_u32 s33, 4
	s_mov_b32 s30, 0x20000
	v_writelane_b32 v244, s7, 55
	s_cselect_b64 s[6:7], -1, 0
	v_writelane_b32 v244, s6, 56
	s_cmp_eq_u32 s33, 3
	s_movk_i32 s78, 0xffb0
	v_writelane_b32 v244, s7, 57
	s_cselect_b64 s[6:7], -1, 0
	v_writelane_b32 v244, s6, 58
	s_cmp_eq_u32 s33, 2
	s_mov_b32 s79, 0xf800000
	v_writelane_b32 v244, s7, 59
	s_cselect_b64 s[6:7], -1, 0
	v_writelane_b32 v244, s6, 60
	s_cmp_eq_u32 s33, 1
	s_movk_i32 s74, 0x1000
	v_writelane_b32 v244, s7, 61
	s_cselect_b64 s[6:7], -1, 0
	v_writelane_b32 v244, s6, 62
	s_cmp_eq_u32 s33, 0
	s_movk_i32 s75, 0xff3f
	v_writelane_b32 v244, s7, 63
	s_cselect_b64 s[6:7], -1, 0
	v_writelane_b32 v243, s6, 0
	s_movk_i32 s88, 0x5e
	s_mov_b32 s89, 0x11b80000
	v_writelane_b32 v243, s7, 1
	s_lshl_b32 s6, s33, 8
	s_add_u32 s0, s0, s6
	s_addc_u32 s1, s1, 0
	s_add_u32 s6, s0, 0x1400
	s_addc_u32 s7, s1, 0
	v_writelane_b32 v243, s6, 2
	s_add_u32 s0, s0, 0x2400
	s_addc_u32 s1, s1, 0
	v_writelane_b32 v243, s7, 3
	v_writelane_b32 v243, s0, 4
	s_movk_i32 s86, 0xfe7f
	s_movk_i32 s31, 0x4100
	v_writelane_b32 v243, s1, 5
	s_add_u32 s0, s68, 0x16374100
	s_addc_u32 s1, s69, 0
	v_writelane_b32 v243, s0, 6
	s_mov_b64 s[60:61], 0x80
	s_mov_b32 s96, s93
	v_writelane_b32 v243, s1, 7
	s_add_u32 s0, s68, 0x16374200
	s_addc_u32 s1, s69, 0
	v_writelane_b32 v243, s0, 8
	s_ashr_i32 s90, s80, 4
	s_ashr_i32 s40, s2, 4
	v_writelane_b32 v243, s1, 9
	s_and_b32 s0, s2, 15
	s_cmpk_lt_i32 s40, 0x82
	s_cselect_b64 s[6:7], -1, 0
	v_writelane_b32 v243, s6, 10
	s_lshl_b32 s1, s0, 14
	s_nop 0
	v_writelane_b32 v243, s7, 11
	v_writelane_b32 v243, s1, 12
	s_lshl_b32 s1, s0, 6
	v_writelane_b32 v243, s1, 13
	s_waitcnt lgkmcnt(0)
	s_mov_b64 s[6:7], s[46:47]
	v_writelane_b32 v243, s4, 14
	s_lshl_b32 s1, s0, 8
	s_add_u32 s38, s44, s1
	v_writelane_b32 v243, s5, 15
	v_writelane_b32 v243, s6, 16
	v_writelane_b32 v243, s7, 17
	s_addc_u32 s39, s45, 0
	s_lshl_b32 s1, s40, 7
	v_writelane_b32 v243, s38, 18
	s_cmp_lt_i32 s40, 2
	s_movk_i32 s6, 0x4100
	v_writelane_b32 v243, s39, 19
	s_cselect_b32 s6, 0x100, s6
	v_writelane_b32 v243, s6, 20
	s_cselect_b32 s6, 0, 0x100
	v_writelane_b32 v243, s6, 21
	v_writelane_b32 v243, s1, 22
	s_add_i32 s1, s1, -2
	v_writelane_b32 v243, s1, 23
	s_add_u32 s1, s68, 0x16370d40
	v_writelane_b32 v243, s1, 24
	s_addc_u32 s1, s69, 0
	s_cmp_lt_i32 s2, 64
	v_writelane_b32 v243, s1, 25
	s_cselect_b64 s[6:7], -1, 0
	s_add_u32 s13, s8, 0x11c80000
	v_writelane_b32 v243, s6, 26
	s_addc_u32 s33, s9, 0
	s_add_u32 s1, s8, 0x2800000
	v_writelane_b32 v243, s7, 27
	v_writelane_b32 v243, s1, 28
	s_addc_u32 s1, s9, 0
	s_add_u32 s38, s8, 0x16374d00
	s_addc_u32 s39, s9, 0
	s_cmpk_lt_i32 s2, 0x200
	v_writelane_b32 v243, s1, 29
	s_cselect_b64 s[6:7], -1, 0
	v_writelane_b32 v243, s6, 30
	s_lshl_b32 s1, s5, 6
	s_lshl_b32 s9, s2, 3
	s_lshl_b32 s10, s80, 3
	v_writelane_b32 v243, s7, 31
	s_cmp_lt_i32 s5, 0
	s_movk_i32 s6, 0xa1
	s_cselect_b32 s6, s6, 0xa0
	s_mul_i32 s6, s5, s6
	s_mulk_i32 s5, 0x41
	s_cselect_b32 s1, s5, s1
	s_add_i32 s6, s6, s4
	s_mul_hi_i32 s5, s6, 0x66666667
	s_lshr_b32 s7, s5, 31
	s_ashr_i32 s5, s5, 6
	s_add_i32 s5, s5, s7
	s_mul_i32 s7, s5, 0xa0
	s_sub_i32 s6, s6, s7
	s_bfe_u32 s7, s6, 0x3001c
	s_add_i32 s7, s6, s7
	s_and_b32 s8, s7, 0xfff8
	s_sub_i32 s6, s6, s8
	s_lshl_b32 s5, s5, 3
	s_sext_i32_i16 s7, s7
	s_sext_i32_i16 s6, s6
	s_add_i32 s42, s5, s6
	s_lshr_b32 s6, s7, 3
	s_ashr_i32 s5, s7, 3
	s_bfe_i64 s[6:7], s[6:7], 0x100000
	v_writelane_b32 v243, s5, 32
	s_lshl_b64 s[6:7], s[6:7], 20
	v_writelane_b32 v243, s6, 33
	s_ashr_i32 s43, s42, 31
	s_nop 0
	v_writelane_b32 v243, s7, 34
	s_mov_b32 s6, s42
	v_writelane_b32 v243, s6, 35
	s_nop 1
	v_writelane_b32 v243, s7, 36
	s_lshl_b64 s[6:7], s[42:43], 20
	s_add_u32 s6, s11, s6
	v_writelane_b32 v243, s11, 37
	s_addc_u32 s7, s12, s7
	v_writelane_b32 v243, s12, 38
	s_add_u32 s42, s6, 0x80000
	v_writelane_b32 v243, s6, 39
	s_addc_u32 s43, s7, 0
	s_add_i32 s1, s1, s4
	s_ashr_i32 s4, s1, 31
	s_lshr_b32 s4, s4, 26
	s_add_i32 s4, s1, s4
	s_and_b32 s5, s4, 0xffc0
	s_sub_i32 s1, s1, s5
	s_bfe_i32 s5, s1, 0x80000
	s_bfe_u32 s5, s5, 0x3000c
	s_add_i32 s5, s1, s5
	v_writelane_b32 v243, s7, 40
	s_and_b32 s6, s5, 0xf8
	s_sub_i32 s1, s1, s6
	s_ashr_i32 s4, s4, 6
	s_bfe_i32 s5, s5, 0x80000
	s_lshl_b32 s4, s4, 3
	s_sext_i32_i16 s5, s5
	s_sext_i32_i8 s1, s1
	v_writelane_b32 v243, s42, 41
	s_add_i32 s6, s4, s1
	s_lshr_b32 s4, s5, 3
	v_writelane_b32 v243, s43, 42
	s_ashr_i32 s1, s5, 3
	s_bfe_i64 s[4:5], s[4:5], 0x100000
	v_writelane_b32 v243, s1, 43
	s_lshl_b64 s[4:5], s[4:5], 20
	v_writelane_b32 v243, s4, 44
	s_ashr_i32 s7, s6, 31
	s_movk_i32 s1, 0x3ff
	v_writelane_b32 v243, s5, 45
	s_mov_b32 s4, s6
	v_writelane_b32 v243, s4, 46
	v_and_or_b32 v0, v0, s1, v175
	s_mul_i32 s1, s81, s3
	v_writelane_b32 v243, s5, 47
	s_lshl_b64 s[4:5], s[6:7], 20
	v_writelane_b32 v243, s13, 48
	s_add_u32 s4, s13, s4
	v_writelane_b32 v243, s33, 49
	s_addc_u32 s5, s33, s5
	v_writelane_b32 v243, s1, 50
	s_add_u32 s6, s4, 0x80000
	v_writelane_b32 v243, s4, 51
	s_addc_u32 s7, s5, 0
	s_ashr_i32 s41, s40, 31
	v_writelane_b32 v243, s5, 52
	s_lshl_b32 s3, s0, 9
	s_lshl_b64 s[0:1], s[40:41], 13
	v_writelane_b32 v243, s6, 53
	s_or_b32 s0, s0, s3
	s_add_u32 s0, s0, 0x16064c40
	v_writelane_b32 v243, s7, 54
	v_writelane_b32 v243, s0, 55
	s_addc_u32 s0, s1, 0
	v_writelane_b32 v243, s0, 56
	s_mov_b32 s0, s40
	v_writelane_b32 v243, s0, 57
	s_load_dwordx4 s[4:7], s[52:53], 0x98
	s_ashr_i32 s91, s90, 31
	v_writelane_b32 v243, s1, 58
	s_add_i32 s0, s40, s90
	v_writelane_b32 v243, s0, 59
	s_lshl_b32 s0, s0, 7
	v_writelane_b32 v243, s0, 60
	s_lshl_b32 s0, s2, 5
	v_writelane_b32 v243, s0, 61
	v_writelane_b32 v243, s9, 62
	s_add_i32 s0, s9, s10
	v_writelane_b32 v243, s0, 63
	s_add_i32 s0, 0, 0x20ff0
	v_writelane_b32 v242, s0, 0
	s_add_i32 s0, 0, 0x20ff4
	v_writelane_b32 v242, s0, 1
	s_add_i32 s0, 0, 0x1ec80
	v_writelane_b32 v242, s0, 2
	s_add_i32 s0, 0, 0x11c80
	v_writelane_b32 v242, s0, 3
	s_add_i32 s0, 0, 0x1a480
	v_writelane_b32 v242, s0, 4
	s_add_i32 s0, 0, 0x17800
	v_writelane_b32 v242, s0, 5
	v_cmp_eq_u32_e64 s[0:1], 0, v0
	s_ashr_i32 s11, s10, 31
	s_lshl_b32 s85, s90, 7
	v_writelane_b32 v242, s0, 6
	s_lshl_b32 s87, s80, 5
	s_mov_b32 s81, 0x30000
	v_writelane_b32 v242, s1, 7
	s_load_dwordx2 s[0:1], s[52:53], 0x58
	s_movk_i32 s3, 0x2000
	s_add_i32 s33, 0, 0x20fe0
	s_waitcnt lgkmcnt(0)
	v_writelane_b32 v242, s0, 8
	s_nop 1
	v_writelane_b32 v242, s1, 9
	s_load_dwordx2 s[0:1], s[52:53], 0x68
	s_waitcnt lgkmcnt(0)
	v_writelane_b32 v242, s0, 10
	s_nop 1
	v_writelane_b32 v242, s1, 11
	s_load_dwordx2 s[0:1], s[52:53], 0xb8
	s_waitcnt lgkmcnt(0)
	v_writelane_b32 v242, s0, 12
	s_nop 1
	v_writelane_b32 v242, s1, 13
	s_lshl_b64 s[0:1], s[90:91], 13
	v_writelane_b32 v242, s0, 14
	s_nop 1
	v_writelane_b32 v242, s1, 15
	s_lshl_b64 s[0:1], s[90:91], 12
	v_writelane_b32 v242, s0, 16
	s_mov_b32 s91, 0x40000
	s_nop 0
	v_writelane_b32 v242, s1, 17
	s_lshl_b64 s[0:1], s[10:11], 2
	v_writelane_b32 v242, s0, 18
	s_nop 1
	v_writelane_b32 v242, s1, 19
	v_writelane_b32 v242, s10, 20
	s_lshl_b64 s[0:1], s[10:11], 12
	s_nop 0
	v_writelane_b32 v242, s11, 21
	v_writelane_b32 v242, s0, 22
	s_nop 1
	v_writelane_b32 v242, s1, 23
	s_load_dwordx2 s[0:1], s[52:53], 0xa8
	s_waitcnt lgkmcnt(0)
	v_writelane_b32 v242, s0, 24
	s_nop 1
	v_writelane_b32 v242, s1, 25
	v_writelane_b32 v242, s4, 26
	s_nop 1
	v_writelane_b32 v242, s5, 27
	v_writelane_b32 v242, s6, 28
	v_writelane_b32 v242, s7, 29
	v_writelane_b32 v242, s52, 30
	s_load_dwordx8 s[4:11], s[52:53], 0x78
	s_nop 0
	v_writelane_b32 v242, s53, 31
	s_waitcnt lgkmcnt(0)
	v_writelane_b32 v242, s4, 32
	s_nop 1
	v_writelane_b32 v242, s5, 33
	v_writelane_b32 v242, s6, 34
	v_writelane_b32 v242, s7, 35
	v_writelane_b32 v242, s8, 36
	v_writelane_b32 v242, s9, 37
	v_writelane_b32 v242, s10, 38
	v_writelane_b32 v242, s11, 39
	v_writelane_b32 v242, s14, 40
	s_mov_b64 s[10:11], -1
	s_nop 0
	v_writelane_b32 v242, s15, 41
	v_writelane_b32 v242, s16, 42
	s_nop 1
	v_writelane_b32 v242, s17, 43
	v_writelane_b32 v242, s58, 44
	s_nop 1
	v_writelane_b32 v242, s59, 45
	v_writelane_b32 v242, s87, 46
	s_branch .LBB0_222

.LBB0_241:
	s_cmp_eq_u32 s8, 1
	s_cbranch_scc0 .Lsb_aA_skip
	s_waitcnt vmcnt(0)
	s_barrier
	s_barrier
	s_and_saveexec_b64 s[100:101], s[56:57]
	s_cbranch_execz .Lsb_aA_x
	v_readlane_b32 s98, v242, 47
	s_nop 3
	s_cmp_eq_u32 s98, 0
	s_cselect_b32 s99, 0, 128
	s_getreg_b32 s98, hwreg(HW_REG_XCC_ID, 0, 4)
	s_lshl_b32 s98, s98, 2
	s_add_u32 s98, s98, s99
	s_add_u32 s98, s98, 0x16370e00
	s_add_u32 s98, s68, s98
	s_addc_u32 s99, s69, 0
	v_mov_b32_e32 v246, 0
	v_mov_b32_e32 v247, 1
	global_atomic_add v247, v246, v247, s[98:99] sc0
	v_mov_b32_e32 v246, 0x20ff0
	ds_read_b32 v246, v246
	s_waitcnt vmcnt(0) lgkmcnt(0)
	v_add_u32_e32 v247, 1, v247
	v_cmp_eq_u32_e32 vcc, v247, v246
	s_cbranch_vccz .Lsb_aA_x
	buffer_wbl2 sc1
	s_waitcnt vmcnt(0)
	v_readlane_b32 s98, v242, 47
	s_nop 3
	s_cmp_eq_u32 s98, 0
	s_cselect_b32 s98, 0, 8
	s_add_u32 s98, s98, 0x16370d00
	s_add_u32 s98, s68, s98
	s_addc_u32 s99, s69, 0
	v_mov_b32_e32 v246, 0
	v_mov_b32_e32 v247, 1
	global_atomic_add v246, v247, s[98:99]
	s_waitcnt vmcnt(0)
.Lsb_aA_x:
	s_or_b64 exec, exec, s[100:101]
.Lsb_aA_skip:
	s_andn2_b64 vcc, exec, s[42:43]
	s_mov_b32 s10, s50
	s_mov_b32 s9, s52
	s_mov_b64 s[72:73], s[58:59]
	s_mov_b64 s[42:43], s[54:55]
	s_cbranch_vccz .LBB0_251

.LBB0_263:
	s_mul_i32 s0, s96, 5
	s_add_i32 s4, s0, 3
	s_waitcnt vmcnt(0)
	s_barrier
	s_and_saveexec_b64 s[100:101], s[56:57]
	s_cbranch_execz .Lsb_aB_x
	v_readlane_b32 s98, v242, 47
	s_nop 3
	s_cmp_eq_u32 s98, 0
	s_cselect_b32 s99, 0, 128
	s_getreg_b32 s98, hwreg(HW_REG_XCC_ID, 0, 4)
	s_lshl_b32 s98, s98, 2
	s_add_u32 s98, s98, s99
	s_add_u32 s98, s98, 0x16370e40
	s_add_u32 s98, s68, s98
	s_addc_u32 s99, s69, 0
	v_mov_b32_e32 v246, 0
	v_mov_b32_e32 v247, 1
	global_atomic_add v247, v246, v247, s[98:99] sc0
	v_mov_b32_e32 v246, 0x20ff0
	ds_read_b32 v246, v246
	s_waitcnt vmcnt(0) lgkmcnt(0)
	v_add_u32_e32 v247, 1, v247
	v_cmp_eq_u32_e32 vcc, v247, v246
	s_cbranch_vccz .Lsb_aB_x
	buffer_wbl2 sc1
	s_waitcnt vmcnt(0)
	v_readlane_b32 s98, v242, 47
	s_nop 3
	s_cmp_eq_u32 s98, 0
	s_cselect_b32 s98, 0, 8
	s_add_u32 s98, s98, 0x16370d04
	s_add_u32 s98, s68, s98
	s_addc_u32 s99, s69, 0
	v_mov_b32_e32 v246, 0
	v_mov_b32_e32 v247, 1
	global_atomic_add v246, v247, s[98:99]
	s_waitcnt vmcnt(0)
.Lsb_aB_x:
	s_or_b64 exec, exec, s[100:101]
	s_and_saveexec_b64 s[100:101], s[56:57]
	s_cbranch_execz .Lsb_wA_x
	v_readlane_b32 s98, v242, 47
	s_nop 3
	s_cmp_eq_u32 s98, 0
	s_cselect_b32 s98, 0, 8
	s_add_u32 s98, s98, 0x16370d00
	s_add_u32 s98, s68, s98
	s_addc_u32 s99, s69, 0
	v_mov_b32_e32 v247, 0x20ff4
	ds_read_b32 v247, v247
	v_mov_b32_e32 v245, 0
	s_waitcnt lgkmcnt(0)
.Lsb_wA_s:
	v_mov_b32_e32 v246, 0
	global_load_dword v246, v246, s[98:99] sc1
	s_waitcnt vmcnt(0)
	v_cmp_lt_u32_e32 vcc, v246, v247
	s_cbranch_vccz .Lsb_wA_g
	s_sleep 2
	v_add_u32_e32 v245, 1, v245
	v_cmp_gt_u32_e32 vcc, 0x4000, v245
	s_cbranch_vccnz .Lsb_wA_s
.Lsb_wA_g:
	buffer_inv sc1
	s_waitcnt vmcnt(0)
.Lsb_wA_x:
	s_or_b64 exec, exec, s[100:101]
	v_mov_b32_e32 v245, 0xc0135761
	s_barrier
	s_branch .LBB0_329
	s_cmp_ge_i32 s4, s71
	s_cbranch_scc1 .LBB0_329
	v_readlane_b32 s0, v244, 18
	v_readlane_b32 s1, v244, 19
	s_andn2_b64 vcc, exec, s[0:1]
	s_cbranch_vccnz .LBB0_276
	s_barrier
	s_mov_b64 s[0:1], exec
	v_readlane_b32 s6, v242, 6
	v_readlane_b32 s7, v242, 7
	s_and_b64 s[6:7], s[0:1], s[6:7]
	s_mov_b64 exec, s[6:7]
	s_cbranch_execz .LBB0_275
	v_readlane_b32 s6, v244, 0
	v_readlane_b32 s7, v244, 1
	buffer_wbl2 sc1
	s_waitcnt vmcnt(0)
	s_load_dwordx2 s[40:41], s[6:7], 0x58
	s_mov_b64 s[42:43], exec
	v_mbcnt_lo_u32_b32 v1, s42, 0
	v_mbcnt_hi_u32_b32 v1, s43, v1
	v_cmp_eq_u32_e32 vcc, 0, v1
	s_waitcnt lgkmcnt(0)
	global_load_dword v0, v145, s[40:41] offset:40
	s_and_saveexec_b64 s[44:45], vcc
	s_cbranch_execz .LBB0_268
	s_bcnt1_i32_b64 s5, s[42:43]
	v_mov_b32_e32 v2, s5
	global_atomic_add v2, v145, v2, s[40:41] offset:32 sc0

.LBB0_361:
	s_waitcnt vmcnt(0)
	s_barrier
	s_and_saveexec_b64 s[100:101], s[56:57]
	s_and_b32 s98, s2, 15
	s_lshl_b32 s99, s96, 4
	s_add_i32 s98, s98, s99
	s_lshl_b32 s98, s98, 2
	s_add_u32 s98, s98, 0x16370d80
	s_add_u32 s98, s68, s98
	s_addc_u32 s99, s69, 0
	v_mov_b32_e32 v246, 0
	v_mov_b32_e32 v247, 1
	global_atomic_add v246, v247, s[98:99]
	s_or_b64 exec, exec, s[100:101]
	s_and_saveexec_b64 s[100:101], s[56:57]
	s_cbranch_execz .Lsb_wB_x
	v_readlane_b32 s98, v242, 47
	s_nop 3
	s_cmp_eq_u32 s98, 0
	s_cselect_b32 s98, 0, 8
	s_add_u32 s98, s98, 0x16370d04
	s_add_u32 s98, s68, s98
	s_addc_u32 s99, s69, 0
	v_mov_b32_e32 v247, 0x20ff4
	ds_read_b32 v247, v247
	v_mov_b32_e32 v245, 0
	s_waitcnt lgkmcnt(0)

.Lsb_wB_x:
	s_or_b64 exec, exec, s[100:101]
	v_mov_b32_e32 v245, 0xc0135761
	s_barrier
	v_writelane_b32 v242, s10, 48
	s_and_b64 s[0:1], s[10:11], exec
	s_cselect_b32 s87, 0, 4
	s_lshl_b32 s92, s96, 1
	s_xor_b32 s91, s87, 0x104
	s_lshl_b64 s[0:1], s[92:93], 2
	v_readlane_b32 s4, v243, 24
	s_add_u32 s46, s4, s0
	v_readlane_b32 s0, v243, 25
	s_addc_u32 s47, s0, s1
	s_lshl_b32 s0, s87, 1
	v_writelane_b32 v242, s11, 49
	s_addk_i32 s0, 0xfefc
	v_writelane_b32 v242, s0, 51
	s_mul_i32 s92, s96, 0x3e00
	v_readlane_b32 s4, v242, 32
	s_lshl_b32 s97, s91, 1
	s_cmp_eq_u32 s87, 0
	s_cselect_b32 s98, 8, 0
	s_add_i32 s97, s97, s98
	s_lshl_b64 s[0:1], s[92:93], 2
	v_readlane_b32 s6, v242, 34
	v_readlane_b32 s7, v242, 35
	s_add_u32 s50, s6, s0
	v_readlane_b32 s5, v242, 33
	s_addc_u32 s51, s7, s1
	s_lshl_b32 s52, s96, 9
	s_mov_b32 s53, s93
	v_readlane_b32 s10, v242, 38
	s_lshl_b64 s[4:5], s[52:53], 2
	v_readlane_b32 s11, v242, 39
	s_add_u32 s54, s10, s4
	s_addc_u32 s55, s11, s5
	v_readlane_b32 s12, v242, 26
	v_readlane_b32 s13, v242, 27
	s_add_u32 s58, s12, s4
	v_readlane_b32 s14, v242, 28
	s_addc_u32 s59, s13, s5
	s_lshl_b32 s53, s96, 3
	v_readlane_b32 s15, v242, 29
	s_add_u32 s0, s14, s4
	s_addc_u32 s1, s15, s5
	v_readlane_b32 s6, v242, 24
	v_readlane_b32 s7, v242, 25
	s_add_u32 s72, s6, s4
	s_addc_u32 s73, s7, s5
	v_readlane_b32 s8, v242, 36
	v_readlane_b32 s9, v242, 37
	s_branch .LBB0_364
